# GLA prep token loop: q/k loads of the next 8-token group issued one iteration ahead (register double-buffer), body vmcnt waits removed
# baseline (speedup 1.0000x reference)
; #define LAS __attribute__((address_space(3)))
; __device__ __forceinline__ void ph_prep(Frame& F, int e) {
;     ...
;         for (int i = 0; i < 16; ++i) wfb[i] = (pg8::f32x2){w2[i * 512 + col], w2[(16 + i) * 512 + col]} * 1.4426950408889634f;
;         bfb = (pg8::f32x2){bg[col], bg[512 + col]} * 1.4426950408889634f;
;         __syncthreads();
;         if (F.tid < 256) { const int row = F.tid >> 2, part = F.tid & 3; const v4u w = *(const v4u*)(Prow0 + (size_t)row * DINP + C_AB + 8 * part);
;             LAS float* d = ABf + row * 32 + 16 * (part & 1) + (part >> 1);
;             d[0] = bflo(w.x); d[2] = bfhi(w.x); d[4] = bflo(w.y); d[6] = bfhi(w.y); d[8] = bflo(w.z); d[10] = bfhi(w.z); d[12] = bflo(w.w); d[14] = bfhi(w.w); }
;         __syncthreads();
;         if (!active) continue;
;         const int prw = rc & 63;
;         float pf = 0.f, pbx = 0.f;
;         for (int t8 = 0; t8 < 64; t8 += 8) {
;             float qv[8], kv[8];
; #pragma unroll
;             for (int tt = 0; tt < 8; ++tt) { const bf16* prow = Prow0 + (size_t)(t8 + tt) * DINP; qv[tt] = bf2f(prow[C_QB + col]); kv[tt] = bf2f(prow[C_KB + col]); }
.LBB0_594:
	s_or_b64 exec, exec, s[40:41]
	s_or_b64 s[40:41], s[52:53], s[50:51]
	s_andn2_b64 vcc, exec, s[40:41]
	s_waitcnt lgkmcnt(0)
	s_barrier
	s_cbranch_vccnz .LBB0_591
	s_add_u32 s40, s19, s57
	s_addc_u32 s41, s20, s56
	v_lshl_add_u64 v[78:79], v[42:43], 1, s[40:41]
	global_load_ushort v106, v[78:79], off
	global_load_ushort v107, v[78:79], off offset:1024
	v_add_co_u32_e32 v122, vcc, 0x3000, v78
	s_nop 1
	v_addc_co_u32_e32 v123, vcc, 0, v79, vcc
	global_load_ushort v108, v[122:123], off offset:512
	global_load_ushort v109, v[122:123], off offset:1536
	v_add_co_u32_e32 v124, vcc, 0x6000, v78
	s_nop 1
	v_addc_co_u32_e32 v125, vcc, 0, v79, vcc
	global_load_ushort v110, v[124:125], off offset:1024
	global_load_ushort v111, v[124:125], off offset:2048
	v_add_co_u32_e32 v126, vcc, 0x9000, v78
	s_nop 1
	v_addc_co_u32_e32 v127, vcc, 0, v79, vcc
	global_load_ushort v112, v[126:127], off offset:1536
	global_load_ushort v113, v[126:127], off offset:2560
	v_add_co_u32_e32 v128, vcc, 0xc000, v78
	s_nop 1
	v_addc_co_u32_e32 v129, vcc, 0, v79, vcc
	global_load_ushort v114, v[128:129], off offset:2048
	global_load_ushort v115, v[128:129], off offset:3072
	v_add_co_u32_e32 v122, vcc, 0xf000, v78
	s_nop 1
	v_addc_co_u32_e32 v123, vcc, 0, v79, vcc
	global_load_ushort v116, v[122:123], off offset:2560
	global_load_ushort v117, v[122:123], off offset:3584
	v_add_co_u32_e32 v124, vcc, 0x12000, v78
	s_nop 1
	v_addc_co_u32_e32 v125, vcc, 0, v79, vcc
	global_load_ushort v118, v[124:125], off offset:3072
	v_add_co_u32_e32 v126, vcc, 0x13000, v78
	s_nop 1
	v_addc_co_u32_e32 v127, vcc, 0, v79, vcc
	global_load_ushort v119, v[126:127], off
	v_add_co_u32_e32 v128, vcc, 0x15000, v78
	s_nop 1
	v_addc_co_u32_e32 v129, vcc, 0, v79, vcc
	global_load_ushort v120, v[128:129], off offset:3584
	v_add_co_u32_e32 v122, vcc, 0x16000, v78
	s_nop 1
	v_addc_co_u32_e32 v123, vcc, 0, v79, vcc
	global_load_ushort v121, v[122:123], off offset:512
	v_add_co_u32_e32 v78, vcc, 0x19000, v78
	s_nop 1
	v_addc_co_u32_e32 v79, vcc, 0, v79, vcc
	s_mov_b32 s30, 0x3fb8aa3b
	s_ashr_i32 s55, s54, 31
	v_pk_mul_f32 v[44:45], v[4:5], s[30:31] op_sel_hi:[1,0]
	v_pk_mul_f32 v[46:47], v[6:7], s[30:31] op_sel_hi:[1,0]
	v_pk_mul_f32 v[48:49], v[8:9], s[30:31] op_sel_hi:[1,0]
	v_pk_mul_f32 v[50:51], v[10:11], s[30:31] op_sel_hi:[1,0]
	v_pk_mul_f32 v[52:53], v[12:13], s[30:31] op_sel_hi:[1,0]
	v_pk_mul_f32 v[54:55], v[14:15], s[30:31] op_sel_hi:[1,0]
	v_pk_mul_f32 v[56:57], v[18:19], s[30:31] op_sel_hi:[1,0]
	v_pk_mul_f32 v[58:59], v[20:21], s[30:31] op_sel_hi:[1,0]
	v_pk_mul_f32 v[60:61], v[22:23], s[30:31] op_sel_hi:[1,0]
	v_pk_mul_f32 v[62:63], v[26:27], s[30:31] op_sel_hi:[1,0]
	v_pk_mul_f32 v[64:65], v[28:29], s[30:31] op_sel_hi:[1,0]
	v_pk_mul_f32 v[66:67], v[30:31], s[30:31] op_sel_hi:[1,0]
	v_pk_mul_f32 v[68:69], v[32:33], s[30:31] op_sel_hi:[1,0]
	v_pk_mul_f32 v[70:71], v[34:35], s[30:31] op_sel_hi:[1,0]
	v_pk_mul_f32 v[72:73], v[24:25], s[30:31] op_sel_hi:[1,0]
	v_pk_mul_f32 v[74:75], v[74:75], s[30:31] op_sel_hi:[1,0]
	v_pk_mul_f32 v[76:77], v[16:17], s[30:31] op_sel_hi:[1,0]
	s_and_b32 s30, s54, 63
	v_mov_b32_e32 v80, 0
	v_lshl_add_u32 v2, s54, 15, v42
	s_mov_b32 s57, 0
	s_mov_b32 s56, 0
	v_mov_b32_e32 v81, v80
	s_waitcnt vmcnt(0)
	s_branch .LBB0_597

; __device__ __forceinline__ unsigned cvt_pk_bf16(float lo, float hi) { unsigned r; asm volatile("v_cvt_pk_bf16_f32 %0, %1, %2" : "=v"(r) : "v"(lo), "v"(hi)); return r; }
; __device__ __forceinline__ float logsig16(float z2) { return (fminf(z2, 0.f) - __builtin_amdgcn_logf(1.0f + __builtin_amdgcn_exp2f(-fabsf(z2)))) * (1.0f / 16.0f); }
; __device__ __forceinline__ void ph_prep(Frame& F, int e) {
;     ...
;         for (int t8 = 0; t8 < 64; t8 += 8) {
;             float qv[8], kv[8];
; #pragma unroll
;             for (int tt = 0; tt < 8; ++tt) { const bf16* prow = Prow0 + (size_t)(t8 + tt) * DINP; qv[tt] = bf2f(prow[C_QB + col]); kv[tt] = bf2f(prow[C_KB + col]); }
; #pragma unroll
;             for (int tt = 0; tt < 8; ++tt) {
;                 const int t = t8 + tt;
;                 float zf, zb; GLA_Z(t, zf, zb);
;                 const float gf = logsig16(zf), gb = logsig16(zb);
;                 pf += gf; const float cumf = pf, pbe = pbx; pbx += gb;
;                 float q = qv[tt], k = kv[tt];
;                 float qp, kp;
;                 { const unsigned uq = __builtin_bit_cast(unsigned, q), uk = __builtin_bit_cast(unsigned, k);
;                   const auto rq = __builtin_amdgcn_permlane16_swap(uq, uq, false, false); const auto rk = __builtin_amdgcn_permlane16_swap(uk, uk, false, false);
;                   qp = __builtin_bit_cast(float, (dk & 16) ? rq[0] : rq[1]); kp = __builtin_bit_cast(float, (dk & 16) ? rk[0] : rk[1]); }
;                 if (lat) { const int ri = (hf ? t : prw) * 16 + f; const float c = RTc[ri], s = RTs[ri];
;                     const float ss = s * sgn; q = fmaf(qp, ss, q * c); k = fmaf(kp, ss, k * c); }
;                 q *= 0.125f;
;                 const unsigned o = (unsigned)((rc * 64 + t) * 512 + col);
;                 const unsigned wq = pg8::cvt_pk_bf16(q * __builtin_amdgcn_exp2f(cumf), q * __builtin_amdgcn_exp2f(fminf(-pbe, 115.f))), wk = pg8::cvt_pk_bf16(k * __builtin_amdgcn_exp2f(fminf(-cumf, 115.f)), k * __builtin_amdgcn_exp2f(pbe));
;                 QF[o] = (bf16)(wq & 0xffffu); QB[o] = (bf16)(wq >> 16); KF[o] = (bf16)(wk & 0xffffu); KB[o] = (bf16)(wk >> 16);
.LBB0_597:
	s_waitcnt vmcnt(32)
	v_mov_b32_e32 v84, v106
	v_mov_b32_e32 v85, v107
	v_mov_b32_e32 v82, v108
	v_mov_b32_e32 v83, v109
	v_mov_b32_e32 v99, v110
	v_mov_b32_e32 v100, v111
	v_mov_b32_e32 v97, v112
	v_mov_b32_e32 v98, v113
	v_mov_b32_e32 v95, v114
	v_mov_b32_e32 v96, v115
	v_mov_b32_e32 v93, v116
	v_mov_b32_e32 v94, v117
	v_mov_b32_e32 v91, v118
	v_mov_b32_e32 v92, v119
	v_mov_b32_e32 v41, v120
	v_mov_b32_e32 v90, v121
	v_add_co_u32_e32 v4, vcc, 0x3000, v78
	s_mov_b32 s40, 0xc000
	s_nop 0
	v_addc_co_u32_e32 v5, vcc, 0, v79, vcc
	v_add_co_u32_e32 v6, vcc, 0x6000, v78
	global_load_ushort v106, v[78:79], off
	global_load_ushort v107, v[78:79], off offset:1024
	v_addc_co_u32_e32 v7, vcc, 0, v79, vcc
	v_add_co_u32_e32 v8, vcc, 0x9000, v78
	v_cndmask_b32_e64 v103, 0, 1, s[52:53]
	s_nop 0
	v_addc_co_u32_e32 v9, vcc, 0, v79, vcc
	v_add_co_u32_e32 v10, vcc, s40, v78
	v_cmp_ne_u32_e64 s[40:41], 1, v103
	s_nop 0
	v_addc_co_u32_e32 v11, vcc, 0, v79, vcc
	global_load_ushort v108, v[4:5], off offset:512
	global_load_ushort v109, v[4:5], off offset:1536
	global_load_ushort v110, v[6:7], off offset:1024
	global_load_ushort v111, v[6:7], off offset:2048
	global_load_ushort v112, v[8:9], off offset:1536
	global_load_ushort v113, v[8:9], off offset:2560
	global_load_ushort v114, v[10:11], off offset:2048
	global_load_ushort v115, v[10:11], off offset:3072
	v_add_co_u32_e32 v4, vcc, 0xf000, v78
	v_lshlrev_b32_e32 v84, 16, v84
	v_addc_co_u32_e32 v5, vcc, 0, v79, vcc
	v_add_co_u32_e32 v6, vcc, 0x12000, v78
	v_lshlrev_b32_e32 v85, 16, v85
	v_addc_co_u32_e32 v7, vcc, 0, v79, vcc
	v_add_co_u32_e32 v8, vcc, 0x13000, v78
	v_mov_b32_e32 v86, v84
	s_nop 0
	v_addc_co_u32_e32 v9, vcc, 0, v79, vcc
	v_add_co_u32_e32 v10, vcc, 0x15000, v78
	v_mov_b32_e32 v87, v84
	s_nop 0
	v_addc_co_u32_e32 v11, vcc, 0, v79, vcc
	v_add_co_u32_e32 v12, vcc, 0x16000, v78
	v_mov_b32_e32 v101, v85
	s_nop 0
	v_addc_co_u32_e32 v13, vcc, 0, v79, vcc
	global_load_ushort v116, v[4:5], off offset:2560
	global_load_ushort v117, v[4:5], off offset:3584
	global_load_ushort v118, v[6:7], off offset:3072
	global_load_ushort v119, v[8:9], off
	global_load_ushort v120, v[10:11], off offset:3584
	global_load_ushort v121, v[12:13], off offset:512
	v_mov_b32_e32 v4, s56
	ds_read_b128 v[32:35], v4
	ds_read_b128 v[28:31], v4 offset:16
	ds_read_b128 v[24:27], v4 offset:32
	ds_read_b128 v[20:23], v4 offset:48
	ds_read_b128 v[16:19], v4 offset:64
	ds_read_b128 v[12:15], v4 offset:80
	ds_read_b128 v[8:11], v4 offset:96
	ds_read_b128 v[4:7], v4 offset:112
	v_mov_b32_e32 v102, v85
	v_permlane16_swap_b32_e32 v86, v87
	s_andn2_b64 vcc, exec, s[52:53]
	v_permlane16_swap_b32_e32 v101, v102
	s_cbranch_vccnz .LBB0_599
	v_mov_b32_e32 v103, s57
	v_mov_b32_e32 v104, s30
	v_cndmask_b32_e64 v103, v103, v104, s[6:7]
	v_lshl_or_b32 v103, v103, 6, v89
	v_add_u32_e32 v103, 0, v103
	ds_read2st64_b32 v[104:105], v103 offset0:32 offset1:48
	v_cndmask_b32_e64 v103, v101, v102, s[4:5]
	v_cndmask_b32_e64 v102, v86, v87, s[4:5]
	s_waitcnt lgkmcnt(0)
	v_cndmask_b32_e64 v86, v105, -v105, s[4:5]
	v_pk_mul_f32 v[84:85], v[104:105], v[84:85] op_sel_hi:[0,1]
	v_pk_fma_f32 v[84:85], v[102:103], v[86:87], v[84:85] op_sel_hi:[1,0,1]
.LBB0_599:
	s_waitcnt lgkmcnt(7)
	v_pk_fma_f32 v[32:33], v[44:45], v[32:33], v[76:77]
	v_lshlrev_b32_e32 v83, 16, v83
	v_pk_fma_f32 v[32:33], v[46:47], v[34:35], v[32:33]
	v_lshlrev_b32_e32 v82, 16, v82
	s_waitcnt lgkmcnt(6)
	v_pk_fma_f32 v[28:29], v[48:49], v[28:29], v[32:33]
	s_and_b64 vcc, exec, s[40:41]
	v_pk_fma_f32 v[28:29], v[50:51], v[30:31], v[28:29]
	s_waitcnt lgkmcnt(5)
	v_pk_fma_f32 v[24:25], v[52:53], v[24:25], v[28:29]
	s_nop 0
	v_pk_fma_f32 v[24:25], v[54:55], v[26:27], v[24:25]
	s_waitcnt lgkmcnt(4)
	v_pk_fma_f32 v[20:21], v[56:57], v[20:21], v[24:25]
	s_nop 0
	v_pk_fma_f32 v[20:21], v[58:59], v[22:23], v[20:21]
	s_waitcnt lgkmcnt(3)
	v_pk_fma_f32 v[16:17], v[60:61], v[16:17], v[20:21]
	s_nop 0
	v_pk_fma_f32 v[16:17], v[62:63], v[18:19], v[16:17]
	s_waitcnt lgkmcnt(2)
	v_pk_fma_f32 v[12:13], v[64:65], v[12:13], v[16:17]
	s_nop 0
	v_pk_fma_f32 v[12:13], v[66:67], v[14:15], v[12:13]
	s_waitcnt lgkmcnt(1)
	v_pk_fma_f32 v[8:9], v[68:69], v[8:9], v[12:13]
	s_nop 0
	v_pk_fma_f32 v[8:9], v[70:71], v[10:11], v[8:9]
	s_waitcnt lgkmcnt(0)
	v_pk_fma_f32 v[4:5], v[72:73], v[4:5], v[8:9]
	v_exp_f32_e32 v8, v81
	v_pk_fma_f32 v[4:5], v[74:75], v[6:7], v[4:5]
	s_nop 0
	v_exp_f32_e64 v6, -|v4|
	v_exp_f32_e64 v7, -|v5|
	v_min_f32_e32 v4, 0, v4
	v_min_f32_e32 v5, 0, v5
	v_add_f32_e32 v6, 1.0, v6
	v_add_f32_e32 v7, 1.0, v7
	v_log_f32_e32 v6, v6
	v_log_f32_e32 v7, v7
	s_nop 0
	v_pk_add_f32 v[4:5], v[4:5], v[6:7] neg_lo:[0,1] neg_hi:[0,1]
	v_max_f32_e64 v6, -v81, -v81
	v_pk_fma_f32 v[86:87], v[4:5], s[24:25], v[80:81] op_sel_hi:[1,0,1]
	v_min_f32_e32 v6, 0x42e60000, v6
	v_exp_f32_e32 v4, v86
	v_exp_f32_e32 v6, v6
	v_min_f32_e64 v7, -v86, s29
	v_exp_f32_e32 v7, v7
	v_mul_f32_e32 v5, 0x3e000000, v84
	v_mul_f32_e32 v4, v4, v5
	v_mul_f32_e32 v5, v6, v5
	v_cvt_pk_bf16_f32 v9, v4, v5
	v_mul_f32_e32 v4, v7, v85
	v_mul_f32_e32 v5, v8, v85
	v_cvt_pk_bf16_f32 v8, v4, v5
	v_lshlrev_b64 v[4:5], 1, v[2:3]
	v_lshl_add_u64 v[6:7], s[10:11], 0, v[4:5]
	global_store_short v[6:7], v9, off
	v_lshl_add_u64 v[6:7], s[22:23], 0, v[4:5]
	global_store_short_d16_hi v[6:7], v9, off
	v_lshl_add_u64 v[6:7], s[12:13], 0, v[4:5]
	v_lshl_add_u64 v[4:5], s[46:47], 0, v[4:5]
	global_store_short v[6:7], v8, off
	global_store_short_d16_hi v[4:5], v8, off
	v_mov_b32_e32 v4, s56
	ds_read_b128 v[32:35], v4 offset:128
	ds_read_b128 v[28:31], v4 offset:144
	ds_read_b128 v[24:27], v4 offset:160
	ds_read_b128 v[20:23], v4 offset:176
	ds_read_b128 v[16:19], v4 offset:192
	ds_read_b128 v[12:15], v4 offset:208
	ds_read_b128 v[8:11], v4 offset:224
	ds_read_b128 v[4:7], v4 offset:240
	v_mov_b32_e32 v80, v82
	v_mov_b32_e32 v81, v82
	v_mov_b32_e32 v84, v83
	v_mov_b32_e32 v85, v83
	v_permlane16_swap_b32_e32 v80, v81
	s_nop 0
	v_permlane16_swap_b32_e32 v84, v85
	s_cbranch_vccnz .LBB0_601
	s_add_i32 s58, s57, 1
	v_mov_b32_e32 v101, s58
	v_mov_b32_e32 v102, s30
	v_cndmask_b32_e64 v101, v101, v102, s[6:7]
	v_lshl_or_b32 v101, v101, 6, v89
	v_add_u32_e32 v101, 0, v101
	ds_read2st64_b32 v[102:103], v101 offset0:32 offset1:48
	v_cndmask_b32_e64 v85, v84, v85, s[4:5]
	v_cndmask_b32_e64 v84, v80, v81, s[4:5]
	s_waitcnt lgkmcnt(0)
	v_cndmask_b32_e64 v80, v103, -v103, s[4:5]
	v_pk_mul_f32 v[82:83], v[102:103], v[82:83] op_sel_hi:[0,1]
	v_pk_fma_f32 v[82:83], v[84:85], v[80:81], v[82:83] op_sel_hi:[1,0,1]
; __device__ __forceinline__ unsigned cvt_pk_bf16(float lo, float hi) { unsigned r; asm volatile("v_cvt_pk_bf16_f32 %0, %1, %2" : "=v"(r) : "v"(lo), "v"(hi)); return r; }
; __device__ __forceinline__ float logsig16(float z2) { return (fminf(z2, 0.f) - __builtin_amdgcn_logf(1.0f + __builtin_amdgcn_exp2f(-fabsf(z2)))) * (1.0f / 16.0f); }
; #define GLA_Z(t, zf, zb) do { const LAS f32x4* ap = (const LAS f32x4*)(ABf + (t) * 32); pg8::f32x2 z2 = bfb; \
;         _Pragma("unroll") for (int i = 0; i < 8; ++i) { const f32x4 a = ap[i]; z2 = (pg8::f32x2){a.x, a.y} * wfb[2 * i] + z2; z2 = (pg8::f32x2){a.z, a.w} * wfb[2 * i + 1] + z2; } \
;         zf = z2.x; zb = z2.y; } while (0)
; __device__ __forceinline__ void ph_prep(Frame& F, int e) {
;     ...
;             for (int tt = 0; tt < 8; ++tt) {
;                 const int t = t8 + tt;
;                 float zf, zb; GLA_Z(t, zf, zb);
;                 const float gf = logsig16(zf), gb = logsig16(zb);
;                 pf += gf; const float cumf = pf, pbe = pbx; pbx += gb;
;                 float q = qv[tt], k = kv[tt];
;                 float qp, kp;
;                 { const unsigned uq = __builtin_bit_cast(unsigned, q), uk = __builtin_bit_cast(unsigned, k);
;                   const auto rq = __builtin_amdgcn_permlane16_swap(uq, uq, false, false); const auto rk = __builtin_amdgcn_permlane16_swap(uk, uk, false, false);
;                   qp = __builtin_bit_cast(float, (dk & 16) ? rq[0] : rq[1]); kp = __builtin_bit_cast(float, (dk & 16) ? rk[0] : rk[1]); }
;                 if (lat) { const int ri = (hf ? t : prw) * 16 + f; const float c = RTc[ri], s = RTs[ri];
;                     const float ss = s * sgn; q = fmaf(qp, ss, q * c); k = fmaf(kp, ss, k * c); }
;                 q *= 0.125f;
;                 const unsigned o = (unsigned)((rc * 64 + t) * 512 + col);
;                 const unsigned wq = pg8::cvt_pk_bf16(q * __builtin_amdgcn_exp2f(cumf), q * __builtin_amdgcn_exp2f(fminf(-pbe, 115.f))), wk = pg8::cvt_pk_bf16(k * __builtin_amdgcn_exp2f(fminf(-cumf, 115.f)), k * __builtin_amdgcn_exp2f(pbe));
;                 QF[o] = (bf16)(wq & 0xffffu); QB[o] = (bf16)(wq >> 16); KF[o] = (bf16)(wk & 0xffffu); KB[o] = (bf16)(wk >> 16);
.LBB0_601:
	s_waitcnt lgkmcnt(7)
	v_pk_fma_f32 v[32:33], v[44:45], v[32:33], v[76:77]
	v_lshlrev_b32_e32 v81, 16, v100
	v_pk_fma_f32 v[32:33], v[46:47], v[34:35], v[32:33]
	v_lshlrev_b32_e32 v80, 16, v99
	s_waitcnt lgkmcnt(6)
	v_pk_fma_f32 v[28:29], v[48:49], v[28:29], v[32:33]
	s_and_b64 vcc, exec, s[40:41]
	v_pk_fma_f32 v[28:29], v[50:51], v[30:31], v[28:29]
	s_waitcnt lgkmcnt(5)
	v_pk_fma_f32 v[24:25], v[52:53], v[24:25], v[28:29]
	s_nop 0
	v_pk_fma_f32 v[24:25], v[54:55], v[26:27], v[24:25]
	s_waitcnt lgkmcnt(4)
	v_pk_fma_f32 v[20:21], v[56:57], v[20:21], v[24:25]
	s_nop 0
	v_pk_fma_f32 v[20:21], v[58:59], v[22:23], v[20:21]
	s_waitcnt lgkmcnt(3)
	v_pk_fma_f32 v[16:17], v[60:61], v[16:17], v[20:21]
	s_nop 0
	v_pk_fma_f32 v[16:17], v[62:63], v[18:19], v[16:17]
	s_waitcnt lgkmcnt(2)
	v_pk_fma_f32 v[12:13], v[64:65], v[12:13], v[16:17]
	s_nop 0
	v_pk_fma_f32 v[12:13], v[66:67], v[14:15], v[12:13]
	s_waitcnt lgkmcnt(1)
	v_pk_fma_f32 v[8:9], v[68:69], v[8:9], v[12:13]
	s_nop 0
	v_pk_fma_f32 v[8:9], v[70:71], v[10:11], v[8:9]
	s_waitcnt lgkmcnt(0)
	v_pk_fma_f32 v[4:5], v[72:73], v[4:5], v[8:9]
	v_exp_f32_e32 v9, v87
	v_pk_fma_f32 v[4:5], v[74:75], v[6:7], v[4:5]
	s_nop 0
	v_exp_f32_e64 v6, -|v4|
	v_exp_f32_e64 v7, -|v5|
	v_min_f32_e32 v4, 0, v4
	v_min_f32_e32 v5, 0, v5
	v_add_f32_e32 v6, 1.0, v6
	v_add_f32_e32 v7, 1.0, v7
	v_log_f32_e32 v6, v6
	v_log_f32_e32 v7, v7
	s_nop 0
	v_pk_add_f32 v[4:5], v[4:5], v[6:7] neg_lo:[0,1] neg_hi:[0,1]
	s_nop 0
	v_pk_fma_f32 v[84:85], v[4:5], s[24:25], v[86:87] op_sel_hi:[1,0,1]
	v_max_f32_e64 v7, -v87, -v87
	v_exp_f32_e32 v5, v84
	v_min_f32_e32 v7, 0x42e60000, v7
	v_min_f32_e64 v8, -v84, s29
	v_exp_f32_e32 v7, v7
	v_exp_f32_e32 v8, v8
	v_mul_f32_e32 v6, 0x3e000000, v82
	v_mul_f32_e32 v5, v5, v6
	v_mul_f32_e32 v6, v7, v6
	v_cvt_pk_bf16_f32 v10, v5, v6
	v_mul_f32_e32 v5, v8, v83
	v_add_u32_e32 v4, 0x200, v2
	v_mul_f32_e32 v6, v9, v83
	v_cvt_pk_bf16_f32 v8, v5, v6
	v_mov_b32_e32 v5, v3
	v_lshlrev_b64 v[4:5], 1, v[4:5]
	v_lshl_add_u64 v[6:7], s[10:11], 0, v[4:5]
	global_store_short v[6:7], v10, off
	v_lshl_add_u64 v[6:7], s[22:23], 0, v[4:5]
	global_store_short_d16_hi v[6:7], v10, off
	v_lshl_add_u64 v[6:7], s[12:13], 0, v[4:5]
	v_lshl_add_u64 v[4:5], s[46:47], 0, v[4:5]
	global_store_short v[6:7], v8, off
	global_store_short_d16_hi v[4:5], v8, off
	v_mov_b32_e32 v4, s56
	ds_read_b128 v[32:35], v4 offset:256
	ds_read_b128 v[28:31], v4 offset:272
	ds_read_b128 v[24:27], v4 offset:288
	ds_read_b128 v[20:23], v4 offset:304
	ds_read_b128 v[16:19], v4 offset:320
	ds_read_b128 v[12:15], v4 offset:336
	ds_read_b128 v[8:11], v4 offset:352
	ds_read_b128 v[4:7], v4 offset:368
	v_mov_b32_e32 v82, v80
	v_mov_b32_e32 v83, v80
	v_mov_b32_e32 v86, v81
	v_mov_b32_e32 v87, v81
	v_permlane16_swap_b32_e32 v82, v83
	s_nop 0
	v_permlane16_swap_b32_e32 v86, v87
	s_cbranch_vccnz .LBB0_603
	s_add_i32 s58, s57, 2
	v_mov_b32_e32 v99, s58
	v_mov_b32_e32 v100, s30
	v_cndmask_b32_e64 v99, v99, v100, s[6:7]
	v_lshl_or_b32 v99, v99, 6, v89
	v_add_u32_e32 v99, 0, v99
	ds_read2st64_b32 v[100:101], v99 offset0:32 offset1:48
	v_cndmask_b32_e64 v87, v86, v87, s[4:5]
	v_cndmask_b32_e64 v86, v82, v83, s[4:5]
	s_waitcnt lgkmcnt(0)
	v_cndmask_b32_e64 v82, v101, -v101, s[4:5]
	v_pk_mul_f32 v[80:81], v[100:101], v[80:81] op_sel_hi:[0,1]
	v_pk_fma_f32 v[80:81], v[86:87], v[82:83], v[80:81] op_sel_hi:[1,0,1]
.LBB0_603:
	s_waitcnt lgkmcnt(7)
	v_pk_fma_f32 v[32:33], v[44:45], v[32:33], v[76:77]
	v_lshlrev_b32_e32 v83, 16, v98
	v_pk_fma_f32 v[32:33], v[46:47], v[34:35], v[32:33]
	v_lshlrev_b32_e32 v82, 16, v97
	s_waitcnt lgkmcnt(6)
	v_pk_fma_f32 v[28:29], v[48:49], v[28:29], v[32:33]
	s_and_b64 vcc, exec, s[40:41]
	v_pk_fma_f32 v[28:29], v[50:51], v[30:31], v[28:29]
	s_waitcnt lgkmcnt(5)
	v_pk_fma_f32 v[24:25], v[52:53], v[24:25], v[28:29]
	s_nop 0
	v_pk_fma_f32 v[24:25], v[54:55], v[26:27], v[24:25]
	s_waitcnt lgkmcnt(4)
	v_pk_fma_f32 v[20:21], v[56:57], v[20:21], v[24:25]
	s_nop 0
	v_pk_fma_f32 v[20:21], v[58:59], v[22:23], v[20:21]
	s_waitcnt lgkmcnt(3)
	v_pk_fma_f32 v[16:17], v[60:61], v[16:17], v[20:21]
	s_nop 0
	v_pk_fma_f32 v[16:17], v[62:63], v[18:19], v[16:17]
	s_waitcnt lgkmcnt(2)
	v_pk_fma_f32 v[12:13], v[64:65], v[12:13], v[16:17]
	s_nop 0
	v_pk_fma_f32 v[12:13], v[66:67], v[14:15], v[12:13]
	s_waitcnt lgkmcnt(1)
	v_pk_fma_f32 v[8:9], v[68:69], v[8:9], v[12:13]
	s_nop 0
	v_pk_fma_f32 v[8:9], v[70:71], v[10:11], v[8:9]
	s_waitcnt lgkmcnt(0)
	v_pk_fma_f32 v[4:5], v[72:73], v[4:5], v[8:9]
	v_exp_f32_e32 v9, v85
	v_pk_fma_f32 v[4:5], v[74:75], v[6:7], v[4:5]
	s_nop 0
	v_exp_f32_e64 v6, -|v4|
	v_exp_f32_e64 v7, -|v5|
	v_min_f32_e32 v4, 0, v4
	v_min_f32_e32 v5, 0, v5
	v_add_f32_e32 v6, 1.0, v6
	v_add_f32_e32 v7, 1.0, v7
	v_log_f32_e32 v6, v6
	v_log_f32_e32 v7, v7
	s_nop 0
	v_pk_add_f32 v[4:5], v[4:5], v[6:7] neg_lo:[0,1] neg_hi:[0,1]
	s_nop 0
	v_pk_fma_f32 v[86:87], v[4:5], s[24:25], v[84:85] op_sel_hi:[1,0,1]
	v_max_f32_e64 v7, -v85, -v85
	v_exp_f32_e32 v5, v86
	v_min_f32_e32 v7, 0x42e60000, v7
	v_min_f32_e64 v8, -v86, s29
	v_exp_f32_e32 v7, v7
	v_exp_f32_e32 v8, v8
	v_mul_f32_e32 v6, 0x3e000000, v80
	v_mul_f32_e32 v5, v5, v6
	v_mul_f32_e32 v6, v7, v6
	v_cvt_pk_bf16_f32 v10, v5, v6
	v_mul_f32_e32 v5, v8, v81
	v_add_u32_e32 v4, 0x400, v2
	v_mul_f32_e32 v6, v9, v81
	v_cvt_pk_bf16_f32 v8, v5, v6
	v_mov_b32_e32 v5, v3
	v_lshlrev_b64 v[4:5], 1, v[4:5]
	v_lshl_add_u64 v[6:7], s[10:11], 0, v[4:5]
	global_store_short v[6:7], v10, off
	v_lshl_add_u64 v[6:7], s[22:23], 0, v[4:5]
	global_store_short_d16_hi v[6:7], v10, off
	v_lshl_add_u64 v[6:7], s[12:13], 0, v[4:5]
	v_lshl_add_u64 v[4:5], s[46:47], 0, v[4:5]
	global_store_short v[6:7], v8, off
	global_store_short_d16_hi v[4:5], v8, off
	v_mov_b32_e32 v4, s56
	ds_read_b128 v[32:35], v4 offset:384
	ds_read_b128 v[28:31], v4 offset:400
	ds_read_b128 v[24:27], v4 offset:416
	ds_read_b128 v[20:23], v4 offset:432
	ds_read_b128 v[16:19], v4 offset:448
	ds_read_b128 v[12:15], v4 offset:464
	ds_read_b128 v[8:11], v4 offset:480
	ds_read_b128 v[4:7], v4 offset:496
	v_mov_b32_e32 v80, v82
	v_mov_b32_e32 v81, v82
	v_mov_b32_e32 v84, v83
	v_mov_b32_e32 v85, v83
	v_permlane16_swap_b32_e32 v80, v81
	s_nop 0
	v_permlane16_swap_b32_e32 v84, v85
	s_cbranch_vccnz .LBB0_605
	s_add_i32 s58, s57, 3
	v_mov_b32_e32 v97, s58
	v_mov_b32_e32 v98, s30
	v_cndmask_b32_e64 v97, v97, v98, s[6:7]
	v_lshl_or_b32 v97, v97, 6, v89
	v_add_u32_e32 v97, 0, v97
	ds_read2st64_b32 v[98:99], v97 offset0:32 offset1:48
	v_cndmask_b32_e64 v85, v84, v85, s[4:5]
	v_cndmask_b32_e64 v84, v80, v81, s[4:5]
	s_waitcnt lgkmcnt(0)
	v_cndmask_b32_e64 v80, v99, -v99, s[4:5]
	v_pk_mul_f32 v[82:83], v[98:99], v[82:83] op_sel_hi:[0,1]
	v_pk_fma_f32 v[82:83], v[84:85], v[80:81], v[82:83] op_sel_hi:[1,0,1]
; __device__ __forceinline__ unsigned cvt_pk_bf16(float lo, float hi) { unsigned r; asm volatile("v_cvt_pk_bf16_f32 %0, %1, %2" : "=v"(r) : "v"(lo), "v"(hi)); return r; }
; __device__ __forceinline__ float logsig16(float z2) { return (fminf(z2, 0.f) - __builtin_amdgcn_logf(1.0f + __builtin_amdgcn_exp2f(-fabsf(z2)))) * (1.0f / 16.0f); }
; #define GLA_Z(t, zf, zb) do { const LAS f32x4* ap = (const LAS f32x4*)(ABf + (t) * 32); pg8::f32x2 z2 = bfb; \
;         _Pragma("unroll") for (int i = 0; i < 8; ++i) { const f32x4 a = ap[i]; z2 = (pg8::f32x2){a.x, a.y} * wfb[2 * i] + z2; z2 = (pg8::f32x2){a.z, a.w} * wfb[2 * i + 1] + z2; } \
;         zf = z2.x; zb = z2.y; } while (0)
; __device__ __forceinline__ void ph_prep(Frame& F, int e) {
;     ...
;             for (int tt = 0; tt < 8; ++tt) {
;                 const int t = t8 + tt;
;                 float zf, zb; GLA_Z(t, zf, zb);
;                 const float gf = logsig16(zf), gb = logsig16(zb);
;                 pf += gf; const float cumf = pf, pbe = pbx; pbx += gb;
;                 float q = qv[tt], k = kv[tt];
;                 float qp, kp;
;                 { const unsigned uq = __builtin_bit_cast(unsigned, q), uk = __builtin_bit_cast(unsigned, k);
;                   const auto rq = __builtin_amdgcn_permlane16_swap(uq, uq, false, false); const auto rk = __builtin_amdgcn_permlane16_swap(uk, uk, false, false);
;                   qp = __builtin_bit_cast(float, (dk & 16) ? rq[0] : rq[1]); kp = __builtin_bit_cast(float, (dk & 16) ? rk[0] : rk[1]); }
;                 if (lat) { const int ri = (hf ? t : prw) * 16 + f; const float c = RTc[ri], s = RTs[ri];
;                     const float ss = s * sgn; q = fmaf(qp, ss, q * c); k = fmaf(kp, ss, k * c); }
;                 q *= 0.125f;
;                 const unsigned o = (unsigned)((rc * 64 + t) * 512 + col);
;                 const unsigned wq = pg8::cvt_pk_bf16(q * __builtin_amdgcn_exp2f(cumf), q * __builtin_amdgcn_exp2f(fminf(-pbe, 115.f))), wk = pg8::cvt_pk_bf16(k * __builtin_amdgcn_exp2f(fminf(-cumf, 115.f)), k * __builtin_amdgcn_exp2f(pbe));
;                 QF[o] = (bf16)(wq & 0xffffu); QB[o] = (bf16)(wq >> 16); KF[o] = (bf16)(wk & 0xffffu); KB[o] = (bf16)(wk >> 16);
.LBB0_605:
	s_waitcnt lgkmcnt(7)
	v_pk_fma_f32 v[32:33], v[44:45], v[32:33], v[76:77]
	v_lshlrev_b32_e32 v81, 16, v96
	v_pk_fma_f32 v[32:33], v[46:47], v[34:35], v[32:33]
	v_lshlrev_b32_e32 v80, 16, v95
	s_waitcnt lgkmcnt(6)
	v_pk_fma_f32 v[28:29], v[48:49], v[28:29], v[32:33]
	s_and_b64 vcc, exec, s[40:41]
	v_pk_fma_f32 v[28:29], v[50:51], v[30:31], v[28:29]
	s_waitcnt lgkmcnt(5)
	v_pk_fma_f32 v[24:25], v[52:53], v[24:25], v[28:29]
	s_nop 0
	v_pk_fma_f32 v[24:25], v[54:55], v[26:27], v[24:25]
	s_waitcnt lgkmcnt(4)
	v_pk_fma_f32 v[20:21], v[56:57], v[20:21], v[24:25]
	s_nop 0
	v_pk_fma_f32 v[20:21], v[58:59], v[22:23], v[20:21]
	s_waitcnt lgkmcnt(3)
	v_pk_fma_f32 v[16:17], v[60:61], v[16:17], v[20:21]
	s_nop 0
	v_pk_fma_f32 v[16:17], v[62:63], v[18:19], v[16:17]
	s_waitcnt lgkmcnt(2)
	v_pk_fma_f32 v[12:13], v[64:65], v[12:13], v[16:17]
	s_nop 0
	v_pk_fma_f32 v[12:13], v[66:67], v[14:15], v[12:13]
	s_waitcnt lgkmcnt(1)
	v_pk_fma_f32 v[8:9], v[68:69], v[8:9], v[12:13]
	s_nop 0
	v_pk_fma_f32 v[8:9], v[70:71], v[10:11], v[8:9]
	s_waitcnt lgkmcnt(0)
	v_pk_fma_f32 v[4:5], v[72:73], v[4:5], v[8:9]
	v_exp_f32_e32 v9, v87
	v_pk_fma_f32 v[4:5], v[74:75], v[6:7], v[4:5]
	s_nop 0
	v_exp_f32_e64 v6, -|v4|
	v_exp_f32_e64 v7, -|v5|
	v_min_f32_e32 v4, 0, v4
	v_min_f32_e32 v5, 0, v5
	v_add_f32_e32 v6, 1.0, v6
	v_add_f32_e32 v7, 1.0, v7
	v_log_f32_e32 v6, v6
	v_log_f32_e32 v7, v7
	s_nop 0
	v_pk_add_f32 v[4:5], v[4:5], v[6:7] neg_lo:[0,1] neg_hi:[0,1]
	s_nop 0
	v_pk_fma_f32 v[84:85], v[4:5], s[24:25], v[86:87] op_sel_hi:[1,0,1]
	v_max_f32_e64 v7, -v87, -v87
	v_exp_f32_e32 v5, v84
	v_min_f32_e32 v7, 0x42e60000, v7
	v_min_f32_e64 v8, -v84, s29
	v_exp_f32_e32 v7, v7
	v_exp_f32_e32 v8, v8
	v_mul_f32_e32 v6, 0x3e000000, v82
	v_mul_f32_e32 v5, v5, v6
	v_mul_f32_e32 v6, v7, v6
	v_cvt_pk_bf16_f32 v10, v5, v6
	v_mul_f32_e32 v5, v8, v83
	v_add_u32_e32 v4, 0x600, v2
	v_mul_f32_e32 v6, v9, v83
	v_cvt_pk_bf16_f32 v8, v5, v6
	v_mov_b32_e32 v5, v3
	v_lshlrev_b64 v[4:5], 1, v[4:5]
	v_lshl_add_u64 v[6:7], s[10:11], 0, v[4:5]
	global_store_short v[6:7], v10, off
	v_lshl_add_u64 v[6:7], s[22:23], 0, v[4:5]
	global_store_short_d16_hi v[6:7], v10, off
	v_lshl_add_u64 v[6:7], s[12:13], 0, v[4:5]
	v_lshl_add_u64 v[4:5], s[46:47], 0, v[4:5]
	global_store_short v[6:7], v8, off
	global_store_short_d16_hi v[4:5], v8, off
	v_mov_b32_e32 v4, s56
	ds_read_b128 v[32:35], v4 offset:512
	ds_read_b128 v[28:31], v4 offset:528
	ds_read_b128 v[24:27], v4 offset:544
	ds_read_b128 v[20:23], v4 offset:560
	ds_read_b128 v[16:19], v4 offset:576
	ds_read_b128 v[12:15], v4 offset:592
	ds_read_b128 v[8:11], v4 offset:608
	ds_read_b128 v[4:7], v4 offset:624
	v_mov_b32_e32 v82, v80
	v_mov_b32_e32 v83, v80
	v_mov_b32_e32 v86, v81
	v_mov_b32_e32 v87, v81
	v_permlane16_swap_b32_e32 v82, v83
	s_nop 0
	v_permlane16_swap_b32_e32 v86, v87
	s_cbranch_vccnz .LBB0_607
	s_add_i32 s58, s57, 4
	v_mov_b32_e32 v95, s58
	v_mov_b32_e32 v96, s30
	v_cndmask_b32_e64 v95, v95, v96, s[6:7]
	v_lshl_or_b32 v95, v95, 6, v89
	v_add_u32_e32 v95, 0, v95
	ds_read2st64_b32 v[96:97], v95 offset0:32 offset1:48
	v_cndmask_b32_e64 v87, v86, v87, s[4:5]
	v_cndmask_b32_e64 v86, v82, v83, s[4:5]
	s_waitcnt lgkmcnt(0)
	v_cndmask_b32_e64 v82, v97, -v97, s[4:5]
	v_pk_mul_f32 v[80:81], v[96:97], v[80:81] op_sel_hi:[0,1]
	v_pk_fma_f32 v[80:81], v[86:87], v[82:83], v[80:81] op_sel_hi:[1,0,1]
.LBB0_607:
	s_waitcnt lgkmcnt(7)
	v_pk_fma_f32 v[32:33], v[44:45], v[32:33], v[76:77]
	v_lshlrev_b32_e32 v83, 16, v94
	v_pk_fma_f32 v[32:33], v[46:47], v[34:35], v[32:33]
	v_lshlrev_b32_e32 v82, 16, v93
	s_waitcnt lgkmcnt(6)
	v_pk_fma_f32 v[28:29], v[48:49], v[28:29], v[32:33]
	s_and_b64 vcc, exec, s[40:41]
	v_pk_fma_f32 v[28:29], v[50:51], v[30:31], v[28:29]
	s_waitcnt lgkmcnt(5)
	v_pk_fma_f32 v[24:25], v[52:53], v[24:25], v[28:29]
	s_nop 0
	v_pk_fma_f32 v[24:25], v[54:55], v[26:27], v[24:25]
	s_waitcnt lgkmcnt(4)
	v_pk_fma_f32 v[20:21], v[56:57], v[20:21], v[24:25]
	s_nop 0
	v_pk_fma_f32 v[20:21], v[58:59], v[22:23], v[20:21]
	s_waitcnt lgkmcnt(3)
	v_pk_fma_f32 v[16:17], v[60:61], v[16:17], v[20:21]
	s_nop 0
	v_pk_fma_f32 v[16:17], v[62:63], v[18:19], v[16:17]
	s_waitcnt lgkmcnt(2)
	v_pk_fma_f32 v[12:13], v[64:65], v[12:13], v[16:17]
	s_nop 0
	v_pk_fma_f32 v[12:13], v[66:67], v[14:15], v[12:13]
	s_waitcnt lgkmcnt(1)
	v_pk_fma_f32 v[8:9], v[68:69], v[8:9], v[12:13]
	s_nop 0
	v_pk_fma_f32 v[8:9], v[70:71], v[10:11], v[8:9]
	s_waitcnt lgkmcnt(0)
	v_pk_fma_f32 v[4:5], v[72:73], v[4:5], v[8:9]
	v_exp_f32_e32 v9, v85
	v_pk_fma_f32 v[4:5], v[74:75], v[6:7], v[4:5]
	s_nop 0
	v_exp_f32_e64 v6, -|v4|
	v_exp_f32_e64 v7, -|v5|
	v_min_f32_e32 v4, 0, v4
	v_min_f32_e32 v5, 0, v5
	v_add_f32_e32 v6, 1.0, v6
	v_add_f32_e32 v7, 1.0, v7
	v_log_f32_e32 v6, v6
	v_log_f32_e32 v7, v7
	s_nop 0
	v_pk_add_f32 v[4:5], v[4:5], v[6:7] neg_lo:[0,1] neg_hi:[0,1]
	s_nop 0
	v_pk_fma_f32 v[86:87], v[4:5], s[24:25], v[84:85] op_sel_hi:[1,0,1]
	v_max_f32_e64 v7, -v85, -v85
	v_exp_f32_e32 v5, v86
	v_min_f32_e32 v7, 0x42e60000, v7
	v_min_f32_e64 v8, -v86, s29
	v_exp_f32_e32 v7, v7
	v_exp_f32_e32 v8, v8
	v_mul_f32_e32 v6, 0x3e000000, v80
	v_mul_f32_e32 v5, v5, v6
	v_mul_f32_e32 v6, v7, v6
	v_cvt_pk_bf16_f32 v10, v5, v6
	v_mul_f32_e32 v5, v8, v81
	v_add_u32_e32 v4, 0x800, v2
	v_mul_f32_e32 v6, v9, v81
	v_cvt_pk_bf16_f32 v8, v5, v6
	v_mov_b32_e32 v5, v3
	v_lshlrev_b64 v[4:5], 1, v[4:5]
	v_lshl_add_u64 v[6:7], s[10:11], 0, v[4:5]
	global_store_short v[6:7], v10, off
	v_lshl_add_u64 v[6:7], s[22:23], 0, v[4:5]
	global_store_short_d16_hi v[6:7], v10, off
	v_lshl_add_u64 v[6:7], s[12:13], 0, v[4:5]
	v_lshl_add_u64 v[4:5], s[46:47], 0, v[4:5]
	global_store_short v[6:7], v8, off
	global_store_short_d16_hi v[4:5], v8, off
	v_mov_b32_e32 v4, s56
	ds_read_b128 v[32:35], v4 offset:640
	ds_read_b128 v[28:31], v4 offset:656
	ds_read_b128 v[24:27], v4 offset:672
	ds_read_b128 v[20:23], v4 offset:688
	ds_read_b128 v[16:19], v4 offset:704
	ds_read_b128 v[12:15], v4 offset:720
	ds_read_b128 v[8:11], v4 offset:736
	ds_read_b128 v[4:7], v4 offset:752
	v_mov_b32_e32 v80, v82
	v_mov_b32_e32 v81, v82
	v_mov_b32_e32 v84, v83
	v_mov_b32_e32 v85, v83
	v_permlane16_swap_b32_e32 v80, v81
	s_nop 0
	v_permlane16_swap_b32_e32 v84, v85
	s_cbranch_vccnz .LBB0_609
	s_add_i32 s58, s57, 5
	v_mov_b32_e32 v93, s58
	v_mov_b32_e32 v94, s30
	v_cndmask_b32_e64 v93, v93, v94, s[6:7]
	v_lshl_or_b32 v93, v93, 6, v89
	v_add_u32_e32 v93, 0, v93
	ds_read2st64_b32 v[94:95], v93 offset0:32 offset1:48
	v_cndmask_b32_e64 v85, v84, v85, s[4:5]
	v_cndmask_b32_e64 v84, v80, v81, s[4:5]
	s_waitcnt lgkmcnt(0)
	v_cndmask_b32_e64 v80, v95, -v95, s[4:5]
	v_pk_mul_f32 v[82:83], v[94:95], v[82:83] op_sel_hi:[0,1]
	v_pk_fma_f32 v[82:83], v[84:85], v[80:81], v[82:83] op_sel_hi:[1,0,1]
; __device__ __forceinline__ unsigned cvt_pk_bf16(float lo, float hi) { unsigned r; asm volatile("v_cvt_pk_bf16_f32 %0, %1, %2" : "=v"(r) : "v"(lo), "v"(hi)); return r; }
; __device__ __forceinline__ float logsig16(float z2) { return (fminf(z2, 0.f) - __builtin_amdgcn_logf(1.0f + __builtin_amdgcn_exp2f(-fabsf(z2)))) * (1.0f / 16.0f); }
; #define GLA_Z(t, zf, zb) do { const LAS f32x4* ap = (const LAS f32x4*)(ABf + (t) * 32); pg8::f32x2 z2 = bfb; \
;         _Pragma("unroll") for (int i = 0; i < 8; ++i) { const f32x4 a = ap[i]; z2 = (pg8::f32x2){a.x, a.y} * wfb[2 * i] + z2; z2 = (pg8::f32x2){a.z, a.w} * wfb[2 * i + 1] + z2; } \
;         zf = z2.x; zb = z2.y; } while (0)
; __device__ __forceinline__ void ph_prep(Frame& F, int e) {
;     ...
;             for (int tt = 0; tt < 8; ++tt) {
;                 const int t = t8 + tt;
;                 float zf, zb; GLA_Z(t, zf, zb);
;                 const float gf = logsig16(zf), gb = logsig16(zb);
;                 pf += gf; const float cumf = pf, pbe = pbx; pbx += gb;
;                 float q = qv[tt], k = kv[tt];
;                 float qp, kp;
;                 { const unsigned uq = __builtin_bit_cast(unsigned, q), uk = __builtin_bit_cast(unsigned, k);
;                   const auto rq = __builtin_amdgcn_permlane16_swap(uq, uq, false, false); const auto rk = __builtin_amdgcn_permlane16_swap(uk, uk, false, false);
;                   qp = __builtin_bit_cast(float, (dk & 16) ? rq[0] : rq[1]); kp = __builtin_bit_cast(float, (dk & 16) ? rk[0] : rk[1]); }
;                 if (lat) { const int ri = (hf ? t : prw) * 16 + f; const float c = RTc[ri], s = RTs[ri];
;                     const float ss = s * sgn; q = fmaf(qp, ss, q * c); k = fmaf(kp, ss, k * c); }
;                 q *= 0.125f;
;                 const unsigned o = (unsigned)((rc * 64 + t) * 512 + col);
;                 const unsigned wq = pg8::cvt_pk_bf16(q * __builtin_amdgcn_exp2f(cumf), q * __builtin_amdgcn_exp2f(fminf(-pbe, 115.f))), wk = pg8::cvt_pk_bf16(k * __builtin_amdgcn_exp2f(fminf(-cumf, 115.f)), k * __builtin_amdgcn_exp2f(pbe));
;                 QF[o] = (bf16)(wq & 0xffffu); QB[o] = (bf16)(wq >> 16); KF[o] = (bf16)(wk & 0xffffu); KB[o] = (bf16)(wk >> 16);
.LBB0_609:
	s_waitcnt lgkmcnt(7)
	v_pk_fma_f32 v[32:33], v[44:45], v[32:33], v[76:77]
	v_lshlrev_b32_e32 v81, 16, v92
	v_pk_fma_f32 v[32:33], v[46:47], v[34:35], v[32:33]
	v_lshlrev_b32_e32 v80, 16, v91
	s_waitcnt lgkmcnt(6)
	v_pk_fma_f32 v[28:29], v[48:49], v[28:29], v[32:33]
	s_and_b64 vcc, exec, s[40:41]
	v_pk_fma_f32 v[28:29], v[50:51], v[30:31], v[28:29]
	s_waitcnt lgkmcnt(5)
	v_pk_fma_f32 v[24:25], v[52:53], v[24:25], v[28:29]
	s_nop 0
	v_pk_fma_f32 v[24:25], v[54:55], v[26:27], v[24:25]
	s_waitcnt lgkmcnt(4)
	v_pk_fma_f32 v[20:21], v[56:57], v[20:21], v[24:25]
	s_nop 0
	v_pk_fma_f32 v[20:21], v[58:59], v[22:23], v[20:21]
	s_waitcnt lgkmcnt(3)
	v_pk_fma_f32 v[16:17], v[60:61], v[16:17], v[20:21]
	s_nop 0
	v_pk_fma_f32 v[16:17], v[62:63], v[18:19], v[16:17]
	s_waitcnt lgkmcnt(2)
	v_pk_fma_f32 v[12:13], v[64:65], v[12:13], v[16:17]
	s_nop 0
	v_pk_fma_f32 v[12:13], v[66:67], v[14:15], v[12:13]
	s_waitcnt lgkmcnt(1)
	v_pk_fma_f32 v[8:9], v[68:69], v[8:9], v[12:13]
	s_nop 0
	v_pk_fma_f32 v[8:9], v[70:71], v[10:11], v[8:9]
	s_waitcnt lgkmcnt(0)
	v_pk_fma_f32 v[4:5], v[72:73], v[4:5], v[8:9]
	v_exp_f32_e32 v9, v87
	v_pk_fma_f32 v[4:5], v[74:75], v[6:7], v[4:5]
	s_nop 0
	v_exp_f32_e64 v6, -|v4|
	v_exp_f32_e64 v7, -|v5|
	v_min_f32_e32 v4, 0, v4
	v_min_f32_e32 v5, 0, v5
	v_add_f32_e32 v6, 1.0, v6
	v_add_f32_e32 v7, 1.0, v7
	v_log_f32_e32 v6, v6
	v_log_f32_e32 v7, v7
	s_nop 0
	v_pk_add_f32 v[4:5], v[4:5], v[6:7] neg_lo:[0,1] neg_hi:[0,1]
	s_nop 0
	v_pk_fma_f32 v[84:85], v[4:5], s[24:25], v[86:87] op_sel_hi:[1,0,1]
	v_max_f32_e64 v7, -v87, -v87
	v_exp_f32_e32 v5, v84
	v_min_f32_e32 v7, 0x42e60000, v7
	v_min_f32_e64 v8, -v84, s29
	v_exp_f32_e32 v7, v7
	v_exp_f32_e32 v8, v8
	v_mul_f32_e32 v6, 0x3e000000, v82
	v_mul_f32_e32 v5, v5, v6
	v_mul_f32_e32 v6, v7, v6
	v_cvt_pk_bf16_f32 v10, v5, v6
	v_mul_f32_e32 v5, v8, v83
	v_add_u32_e32 v4, 0xa00, v2
	v_mul_f32_e32 v6, v9, v83
	v_cvt_pk_bf16_f32 v8, v5, v6
	v_mov_b32_e32 v5, v3
	v_lshlrev_b64 v[4:5], 1, v[4:5]
	v_lshl_add_u64 v[6:7], s[10:11], 0, v[4:5]
	global_store_short v[6:7], v10, off
	v_lshl_add_u64 v[6:7], s[22:23], 0, v[4:5]
	global_store_short_d16_hi v[6:7], v10, off
	v_lshl_add_u64 v[6:7], s[12:13], 0, v[4:5]
	v_lshl_add_u64 v[4:5], s[46:47], 0, v[4:5]
	global_store_short v[6:7], v8, off
	global_store_short_d16_hi v[4:5], v8, off
	v_mov_b32_e32 v4, s56
	ds_read_b128 v[32:35], v4 offset:768
	ds_read_b128 v[28:31], v4 offset:784
	ds_read_b128 v[24:27], v4 offset:800
	ds_read_b128 v[20:23], v4 offset:816
	ds_read_b128 v[16:19], v4 offset:832
	ds_read_b128 v[12:15], v4 offset:848
	ds_read_b128 v[8:11], v4 offset:864
	ds_read_b128 v[4:7], v4 offset:880
	v_mov_b32_e32 v82, v80
	v_mov_b32_e32 v83, v80
	v_mov_b32_e32 v86, v81
	v_mov_b32_e32 v87, v81
	v_permlane16_swap_b32_e32 v82, v83
	s_nop 0
	v_permlane16_swap_b32_e32 v86, v87
	s_cbranch_vccnz .LBB0_611
	s_add_i32 s58, s57, 6
	v_mov_b32_e32 v91, s58
	v_mov_b32_e32 v92, s30
	v_cndmask_b32_e64 v91, v91, v92, s[6:7]
	v_lshl_or_b32 v91, v91, 6, v89
	v_add_u32_e32 v91, 0, v91
	ds_read2st64_b32 v[92:93], v91 offset0:32 offset1:48
	v_cndmask_b32_e64 v87, v86, v87, s[4:5]
	v_cndmask_b32_e64 v86, v82, v83, s[4:5]
	s_waitcnt lgkmcnt(0)
	v_cndmask_b32_e64 v82, v93, -v93, s[4:5]
	v_pk_mul_f32 v[80:81], v[92:93], v[80:81] op_sel_hi:[0,1]
	v_pk_fma_f32 v[80:81], v[86:87], v[82:83], v[80:81] op_sel_hi:[1,0,1]
.LBB0_611:
	s_waitcnt lgkmcnt(7)
	v_pk_fma_f32 v[32:33], v[44:45], v[32:33], v[76:77]
	v_lshlrev_b32_e32 v83, 16, v90
	v_pk_fma_f32 v[32:33], v[46:47], v[34:35], v[32:33]
	v_lshlrev_b32_e32 v82, 16, v41
	s_waitcnt lgkmcnt(6)
	v_pk_fma_f32 v[28:29], v[48:49], v[28:29], v[32:33]
	v_mov_b32_e32 v41, v82
	v_pk_fma_f32 v[28:29], v[50:51], v[30:31], v[28:29]
	s_and_b64 vcc, exec, s[40:41]
	s_waitcnt lgkmcnt(5)
	v_pk_fma_f32 v[24:25], v[52:53], v[24:25], v[28:29]
	s_nop 0
	v_pk_fma_f32 v[24:25], v[54:55], v[26:27], v[24:25]
	s_waitcnt lgkmcnt(4)
	v_pk_fma_f32 v[20:21], v[56:57], v[20:21], v[24:25]
	s_nop 0
	v_pk_fma_f32 v[20:21], v[58:59], v[22:23], v[20:21]
	s_waitcnt lgkmcnt(3)
	v_pk_fma_f32 v[16:17], v[60:61], v[16:17], v[20:21]
	s_nop 0
	v_pk_fma_f32 v[16:17], v[62:63], v[18:19], v[16:17]
	s_waitcnt lgkmcnt(2)
	v_pk_fma_f32 v[12:13], v[64:65], v[12:13], v[16:17]
	s_nop 0
	v_pk_fma_f32 v[12:13], v[66:67], v[14:15], v[12:13]
	s_waitcnt lgkmcnt(1)
	v_pk_fma_f32 v[8:9], v[68:69], v[8:9], v[12:13]
	s_nop 0
	v_pk_fma_f32 v[8:9], v[70:71], v[10:11], v[8:9]
	s_waitcnt lgkmcnt(0)
	v_pk_fma_f32 v[4:5], v[72:73], v[4:5], v[8:9]
	v_exp_f32_e32 v9, v85
	v_pk_fma_f32 v[4:5], v[74:75], v[6:7], v[4:5]
	s_nop 0
	v_exp_f32_e64 v6, -|v4|
	v_exp_f32_e64 v7, -|v5|
	v_min_f32_e32 v4, 0, v4
	v_min_f32_e32 v5, 0, v5
	v_add_f32_e32 v6, 1.0, v6
	v_add_f32_e32 v7, 1.0, v7
	v_log_f32_e32 v6, v6
	v_log_f32_e32 v7, v7
	s_nop 0
	v_pk_add_f32 v[4:5], v[4:5], v[6:7] neg_lo:[0,1] neg_hi:[0,1]
	s_nop 0
	v_pk_fma_f32 v[86:87], v[4:5], s[24:25], v[84:85] op_sel_hi:[1,0,1]
	v_max_f32_e64 v7, -v85, -v85
	v_exp_f32_e32 v5, v86
	v_min_f32_e32 v7, 0x42e60000, v7
	v_min_f32_e64 v8, -v86, s29
	v_exp_f32_e32 v7, v7
	v_exp_f32_e32 v8, v8
	v_mul_f32_e32 v6, 0x3e000000, v80
	v_mul_f32_e32 v5, v5, v6
	v_mul_f32_e32 v6, v7, v6
	v_cvt_pk_bf16_f32 v10, v5, v6
	v_mul_f32_e32 v5, v8, v81
	v_add_u32_e32 v4, 0xc00, v2
	v_mul_f32_e32 v6, v9, v81
	v_cvt_pk_bf16_f32 v8, v5, v6
	v_mov_b32_e32 v5, v3
	v_lshlrev_b64 v[4:5], 1, v[4:5]
	v_lshl_add_u64 v[6:7], s[10:11], 0, v[4:5]
	global_store_short v[6:7], v10, off
	v_lshl_add_u64 v[6:7], s[22:23], 0, v[4:5]
	global_store_short_d16_hi v[6:7], v10, off
	v_lshl_add_u64 v[6:7], s[12:13], 0, v[4:5]
	v_lshl_add_u64 v[4:5], s[46:47], 0, v[4:5]
	global_store_short v[6:7], v8, off
	global_store_short_d16_hi v[4:5], v8, off
	v_mov_b32_e32 v4, s56
	ds_read_b128 v[32:35], v4 offset:896
	ds_read_b128 v[28:31], v4 offset:912
	ds_read_b128 v[24:27], v4 offset:928
	ds_read_b128 v[20:23], v4 offset:944
	ds_read_b128 v[16:19], v4 offset:960
	ds_read_b128 v[12:15], v4 offset:976
	ds_read_b128 v[8:11], v4 offset:992
	ds_read_b128 v[4:7], v4 offset:1008
	v_mov_b32_e32 v80, v82
	v_mov_b32_e32 v81, v83
	v_mov_b32_e32 v84, v83
	v_permlane16_swap_b32_e32 v41, v80
	s_nop 0
	v_permlane16_swap_b32_e32 v81, v84
	s_cbranch_vccnz .LBB0_596
	s_add_i32 s40, s57, 7
	v_mov_b32_e32 v85, s40
	v_mov_b32_e32 v90, s30
	v_cndmask_b32_e64 v85, v85, v90, s[6:7]
	v_lshl_or_b32 v85, v85, 6, v89
	v_add_u32_e32 v85, 0, v85
	ds_read2st64_b32 v[90:91], v85 offset0:32 offset1:48
	v_cndmask_b32_e64 v81, v81, v84, s[4:5]
	v_cndmask_b32_e64 v80, v41, v80, s[4:5]
	s_waitcnt lgkmcnt(0)
	v_cndmask_b32_e64 v84, v91, -v91, s[4:5]
	v_pk_mul_f32 v[82:83], v[90:91], v[82:83] op_sel_hi:[0,1]
	v_pk_fma_f32 v[82:83], v[80:81], v[84:85], v[82:83] op_sel_hi:[1,0,1]
	s_branch .LBB0_596
